# baseline (speedup 1.0000x reference)
; template <bool HS>
; __device__ __forceinline__ void gemm_tile8(const u16* __restrict__ Ap, const u16* __restrict__ Bp, int K,
;                                            f32x4 (&acc)[2][2][4][2], char* shm, const int tid, const float* hsr = nullptr) {
;   const int wid = tid >> 6, lane = tid & 63, wr = wid >> 2, wc = wid & 3, fr = lane & 15, fq = lane >> 4;
;   int r0, c0, r1, c1;
;   stage_rc(tid * 16, r0, c0);
;   stage_rc(tid * 16 + 8192, r1, c1);
;   const unsigned off0 = (unsigned)(r0 * K + c0) * 2u, off1 = (unsigned)(r1 * K + c1) * 2u;
;   const int wvoff = __builtin_amdgcn_readfirstlane(tid >> 6) * 1024;
;   const u16* A1 = Ap + (size_t)128 * K;
;   const u16* B1p = Bp + (size_t)128 * K;
; #pragma unroll
;   for (int a = 0; a < 2; ++a)
; #pragma unroll
;     for (int b = 0; b < 2; ++b)
; #pragma unroll
;       for (int m = 0; m < 4; ++m)
; #pragma unroll
;         for (int n = 0; n < 2; ++n) acc[a][b][m][n] = f32x4{0.f, 0.f, 0.f, 0.f};
;   const int abase = lds_byte(wr * 64 + fr, fq * 8), bbase = lds_byte(wc * 32 + fr, fq * 8);
;   bf16x8 At[4][2], B0[2][2], B1[2][2];
;   const unsigned lds0 = (unsigned)(size_t)(__attribute__((address_space(3))) char*)shm + (unsigned)wvoff;
.Lf_858:
	s_or_b64 exec, exec, s[0:1]
	v_bfe_i32 v6, v0, 27, 1
	v_lshlrev_b32_e32 v4, 4, v0
	v_lshrrev_b32_e32 v6, 22, v6
	v_add_u32_e32 v6, v4, v6
	v_and_b32_e32 v6, 0xfffffc00, v6
	v_ashrrev_i32_e32 v5, 31, v0
	v_sub_u32_e32 v6, v4, v6
	v_lshrrev_b32_e32 v5, 26, v5
	v_lshrrev_b32_e32 v7, 4, v6
	v_add_u32_e32 v5, v0, v5
	v_bitop3_b32 v7, v7, v6, 32 bitop3:0x6c
	v_ashrrev_i32_e32 v6, 31, v6
	v_ashrrev_i32_e32 v5, 6, v5
	v_lshrrev_b32_e32 v6, 26, v6
	v_lshlrev_b32_e32 v8, 3, v5
	v_add_u32_e32 v6, v7, v6
	v_and_b32_e32 v8, 0x1ffff0, v8
	v_ashrrev_i32_e32 v6, 6, v6
	v_add_u32_e32 v8, v6, v8
	v_mul_i32_i24_e32 v6, 64, v6
	v_add_u32_e32 v4, 0x2000, v4
	v_sub_u32_e32 v6, v7, v6
	v_ashrrev_i32_e32 v7, 31, v4
	v_lshrrev_b32_e32 v7, 22, v7
	v_add_u32_e32 v7, v4, v7
	v_ashrrev_i32_e32 v7, 10, v7
	v_mul_i32_i24_e32 v9, 0x400, v7
	v_sub_u32_e32 v4, v4, v9
	v_lshrrev_b32_e32 v9, 4, v4
	v_bitop3_b32 v4, v9, v4, 32 bitop3:0x6c
	v_ashrrev_i32_e32 v10, 31, v4
	v_lshrrev_b32_e32 v10, 26, v10
	v_add_u32_e32 v10, v4, v10
	v_lshlrev_b32_e32 v9, 3, v7
	v_lshrrev_b32_e32 v11, 6, v10
	v_and_b32_e32 v10, 0xc0, v10
	v_and_b32_e32 v9, 0x1ffff0, v9
	v_lshlrev_b32_e32 v7, 5, v7
	v_sub_u32_e32 v4, v4, v10
	s_ashr_i32 s5, s4, 31
	v_lshlrev_b32_e32 v5, 5, v5
	v_add_u32_e32 v9, v11, v9
	v_and_b32_e32 v7, 32, v7
	v_ashrrev_i16_sdwa v4, v178, sext(v4) dst_sel:DWORD dst_unused:UNUSED_PAD src0_sel:DWORD src1_sel:BYTE_0
	s_lshl_b64 s[0:1], s[4:5], 11
	v_and_b32_e32 v5, 32, v5
	v_ashrrev_i16_sdwa v6, v178, sext(v6) dst_sel:DWORD dst_unused:UNUSED_PAD src0_sel:DWORD src1_sel:BYTE_0
	v_bfe_i32 v4, v4, 0, 16
	v_lshl_or_b32 v7, v9, 10, v7
	s_add_u32 s5, s88, s0
	v_bfe_i32 v6, v6, 0, 16
	v_lshl_or_b32 v5, v8, 10, v5
	v_and_b32_e32 v8, 15, v0
	v_add_lshl_u32 v143, v7, v4, 1
	v_lshlrev_b32_e32 v7, 2, v0
	s_addc_u32 s6, s89, s1
	s_ashr_i32 s3, s2, 31
	v_add_lshl_u32 v144, v5, v6, 1
	v_and_b32_e32 v4, 48, v0
	v_lshlrev_b32_e32 v5, 6, v8
	v_and_b32_e32 v7, 32, v7
	s_lshl_b64 s[10:11], s[2:3], 19
	s_lshl_b32 s3, s7, 10
	v_or_b32_e32 v6, v5, v4
	v_bitop3_b32 v4, v5, v7, v4 bitop3:0x36
	v_lshlrev_b32_e32 v2, 12, v2
	s_movk_i32 s7, 0x3000
	v_lshl_add_u64 v[130:131], v[134:135], 0, s[10:11]
	s_mov_b64 s[10:11], 0x40000
	v_and_or_b32 v145, v2, s7, v4
	s_add_i32 s7, s3, 0
	v_lshl_add_u64 v[132:133], v[130:131], 0, s[10:11]
	s_add_u32 s10, s5, 0x40100
	v_lshlrev_b32_e32 v3, 13, v3
	s_addc_u32 s11, s6, 0
	v_readlane_b32 s12, v254, 34
	v_bitop3_b32 v3, v6, v3, v7 bitop3:0xde
	s_add_u32 s12, s12, s0
	v_readlane_b32 s0, v254, 35
	v_mov_b32_e32 v2, 0
	s_addc_u32 s13, s0, s1
	s_mov_b32 s14, -2
	s_mov_b64 s[0:1], 0
	v_add_u32_e32 v142, 0, v3
	s_waitcnt lgkmcnt(0)
	v_mov_b32_e32 v240, v143
	v_mov_b32_e32 v241, v144
	v_mov_b32_e32 v242, v145
	v_mov_b32_e32 v243, v142
	v_add_u32_e32 v244, 0x10000, v145
	v_add_u32_e32 v245, 0x14000, v145
	v_add_u32_e32 v246, 0x18000, v145
	v_add_u32_e32 v247, 0x1c000, v145
	s_branch .Lffn_in_kinit

; #define WAIT_V(n) asm volatile("s_waitcnt vmcnt(" #n ")" ::: "memory")
; #define WAIT_L(n) asm volatile("s_waitcnt lgkmcnt(" #n ")" ::: "memory")
; #define BAR __builtin_amdgcn_s_barrier()
; #define SCHED __builtin_amdgcn_sched_barrier(0)
; #define STG_A(b, h, kt) stage_half_s(lds0 + ((b) * 2 + (h)) * HT_B, ((h) ? A1 : Ap) + (kt) * BK, off0, off1)
; #define STG_B(b, h, kt) stage_half_s(lds0 + (4 + (b) * 2 + (h)) * HT_B, ((h) ? B1p : Bp) + (kt) * BK, off0, off1)
; #define STG_A(b, h, kt) stage_half_s(lds0 + ((b) * 2 + (h)) * HT_B, ((h) ? A1 : Ap) + (kt) * BK, off0, off1)
; #define STG_B(b, h, kt) stage_half_s(lds0 + (4 + (b) * 2 + (h)) * HT_B, ((h) ? B1p : Bp) + (kt) * BK, off0, off1)
; #define LDA8(b, h) _Pragma("unroll") for (int m = 0; m < 4; ++m) _Pragma("unroll") for (int k = 0; k < 2; ++k) \
;     At[m][k] = *(const bf16x8*)(SA_(shm, b, h) + abase + (m * 2 + k) * 1024)
; #define LDB8(dst, b, h) _Pragma("unroll") for (int n = 0; n < 2; ++n) _Pragma("unroll") for (int k = 0; k < 2; ++k) \
;     dst[n][k] = *(const bf16x8*)(SB_(shm, b, h) + bbase + (n * 2 + k) * 1024)
; template <bool HS>
; __device__ __forceinline__ void gemm_tile8(const u16* __restrict__ Ap, const u16* __restrict__ Bp, int K,
;                                            f32x4 (&acc)[2][2][4][2], char* shm, const int tid, const float* hsr = nullptr) {
;     ...
;   const int nt = K / BK;
;   WAIT_V(0);
;   if (wr == 1) BAR;
;   BAR;
;   BAR;
;   for (int t = 0; t < nt - 2; t += 2) {
;     if constexpr (HS) {
;       if (t > 0 && (t & 7) == 0) {
;         const float* rt = hsr + ((t >> 3) - 1) * 256 + wr * 64 + fq * 4;
; #pragma unroll
;         for (int ai = 0; ai < 2; ++ai)
; #pragma unroll
;           for (int m = 0; m < 4; ++m) {
;             const f32x4 q4 = *(const f32x4*)(rt + ai * 128 + m * 16);
; #pragma unroll
;             for (int bj = 0; bj < 2; ++bj)
; #pragma unroll
;               for (int n = 0; n < 2; ++n) acc[ai][bj][m][n] *= q4;
;             SCHED;
;           }
;       }
;     }
;     LDB8(B0, 0, 0); SCHED; LDA8(0, 0); STG_A(1, 1, t + 1);
;     WAIT_L(8); BAR; WAIT_L(0); MMA8(0, 0, B0); BAR; SCHED;
;     LDB8(B1, 0, 1); STG_B(0, 0, t + 2);
;     BAR; WAIT_L(0); MMA8(0, 1, B1); BAR;
;     LDA8(0, 1); STG_A(0, 0, t + 2);
;     BAR; WAIT_L(0); MMA8(1, 0, B0); BAR; SCHED;
;     STG_B(0, 1, t + 2);
;     WAIT_V(6); BAR; MMA8(1, 1, B1); BAR;
.Lffn_in_kinit:
	v_readfirstlane_b32 s20, v130
	v_readfirstlane_b32 s21, v131
	v_readfirstlane_b32 s22, v132
	v_readfirstlane_b32 s23, v133
	s_mov_b32 s16, s5
	s_mov_b32 s17, s6
	s_mov_b32 s18, s12
	s_mov_b32 s19, s13
	s_barrier
	s_barrier
	ds_read_b128 v[146:149], v244
	ds_read_b128 v[150:153], v244 offset:1024
	ds_read_b128 v[154:157], v244 offset:2048
	ds_read_b128 v[158:161], v244 offset:3072
	ds_read_b128 v[162:165], v142
	ds_read_b128 v[166:169], v142 offset:1024
	ds_read_b128 v[170:173], v142 offset:2048
	ds_read_b128 v[174:177], v142 offset:3072
	ds_read_b128 v[180:183], v142 offset:4096
	ds_read_b128 v[184:187], v142 offset:5120
	ds_read_b128 v[188:191], v142 offset:6144
	ds_read_b128 v[192:195], v142 offset:7168
	ds_read_b128 v[196:199], v245
	ds_read_b128 v[200:203], v245 offset:1024
	ds_read_b128 v[204:207], v245 offset:2048
	ds_read_b128 v[208:211], v245 offset:3072
	s_add_u32 s0, s18, 0x80
	s_addc_u32 s1, s19, 0
	s_add_i32 s3, s7, 0xc000
	s_mov_b32 m0, s3
	s_nop 0
	global_load_lds_dwordx4 v144, s[0:1]
	s_add_i32 s3, s7, 0xe000
	s_mov_b32 m0, s3
	s_nop 0
	global_load_lds_dwordx4 v143, s[0:1]
	s_waitcnt vmcnt(8) lgkmcnt(0)
	s_barrier
	s_setprio 1
	v_mfma_f32_16x16x32_bf16 v[126:129], v[162:165], v[146:149], 0
	v_mfma_f32_16x16x32_bf16 v[122:125], v[162:165], v[154:157], 0
	v_mfma_f32_16x16x32_bf16 v[118:121], v[170:173], v[146:149], 0
	v_mfma_f32_16x16x32_bf16 v[114:117], v[170:173], v[154:157], 0
	v_mfma_f32_16x16x32_bf16 v[110:113], v[180:183], v[146:149], 0
	v_mfma_f32_16x16x32_bf16 v[106:109], v[180:183], v[154:157], 0
	v_mfma_f32_16x16x32_bf16 v[102:105], v[188:191], v[146:149], 0
	v_mfma_f32_16x16x32_bf16 v[98:101], v[188:191], v[154:157], 0
	v_mfma_f32_16x16x32_bf16 v[126:129], v[166:169], v[150:153], v[126:129]
	v_mfma_f32_16x16x32_bf16 v[122:125], v[166:169], v[158:161], v[122:125]
	v_mfma_f32_16x16x32_bf16 v[118:121], v[174:177], v[150:153], v[118:121]
	v_mfma_f32_16x16x32_bf16 v[114:117], v[174:177], v[158:161], v[114:117]
	v_mfma_f32_16x16x32_bf16 v[110:113], v[184:187], v[150:153], v[110:113]
	v_mfma_f32_16x16x32_bf16 v[106:109], v[184:187], v[158:161], v[106:109]
	v_mfma_f32_16x16x32_bf16 v[102:105], v[192:195], v[150:153], v[102:105]
	v_mfma_f32_16x16x32_bf16 v[98:101], v[192:195], v[158:161], v[98:101]
	v_mfma_f32_16x16x32_bf16 v[94:97], v[162:165], v[196:199], 0
	v_mfma_f32_16x16x32_bf16 v[90:93], v[162:165], v[204:207], 0
	v_mfma_f32_16x16x32_bf16 v[86:89], v[170:173], v[196:199], 0
	v_mfma_f32_16x16x32_bf16 v[82:85], v[170:173], v[204:207], 0
	v_mfma_f32_16x16x32_bf16 v[78:81], v[180:183], v[196:199], 0
	v_mfma_f32_16x16x32_bf16 v[74:77], v[180:183], v[204:207], 0
	v_mfma_f32_16x16x32_bf16 v[70:73], v[188:191], v[196:199], 0
	v_mfma_f32_16x16x32_bf16 v[66:69], v[188:191], v[204:207], 0
	v_mfma_f32_16x16x32_bf16 v[94:97], v[166:169], v[200:203], v[94:97]
	v_mfma_f32_16x16x32_bf16 v[90:93], v[166:169], v[208:211], v[90:93]
	v_mfma_f32_16x16x32_bf16 v[86:89], v[174:177], v[200:203], v[86:89]
	v_mfma_f32_16x16x32_bf16 v[82:85], v[174:177], v[208:211], v[82:85]
	v_mfma_f32_16x16x32_bf16 v[78:81], v[184:187], v[200:203], v[78:81]
	v_mfma_f32_16x16x32_bf16 v[74:77], v[184:187], v[208:211], v[74:77]
	v_mfma_f32_16x16x32_bf16 v[70:73], v[192:195], v[200:203], v[70:73]
	v_mfma_f32_16x16x32_bf16 v[66:69], v[192:195], v[208:211], v[66:69]
	s_setprio 0
	s_barrier
	ds_read_b128 v[162:165], v142 offset:16384
	ds_read_b128 v[166:169], v142 offset:17408
	ds_read_b128 v[170:173], v142 offset:18432
	ds_read_b128 v[174:177], v142 offset:19456
	ds_read_b128 v[180:183], v142 offset:20480
	ds_read_b128 v[184:187], v142 offset:21504
	ds_read_b128 v[188:191], v142 offset:22528
	ds_read_b128 v[192:195], v142 offset:23552
	s_add_u32 s0, s20, 0x100
	s_addc_u32 s1, s21, 0
	s_add_i32 s3, s7, 0x10000
	s_mov_b32 m0, s3
	s_nop 0
	global_load_lds_dwordx4 v144, s[0:1]
	s_add_i32 s3, s7, 0x12000
	s_mov_b32 m0, s3
	s_nop 0
	global_load_lds_dwordx4 v143, s[0:1]
	s_add_u32 s0, s16, 0x100
	s_addc_u32 s1, s17, 0
	s_mov_b32 m0, s7
	s_nop 0
	global_load_lds_dwordx4 v144, s[0:1]
	s_add_i32 s3, s7, 0x2000
	s_mov_b32 m0, s3
	s_nop 0
	global_load_lds_dwordx4 v143, s[0:1]
	s_add_u32 s0, s22, 0x100
	s_addc_u32 s1, s23, 0
	s_add_i32 s3, s7, 0x14000
	s_mov_b32 m0, s3
	s_nop 0
	global_load_lds_dwordx4 v144, s[0:1]
	s_add_i32 s3, s7, 0x16000
	s_mov_b32 m0, s3
	s_nop 0
	global_load_lds_dwordx4 v143, s[0:1]
	s_waitcnt vmcnt(8) lgkmcnt(0)
	s_barrier
	s_setprio 1
	v_mfma_f32_16x16x32_bf16 v[62:65], v[162:165], v[146:149], 0
	v_mfma_f32_16x16x32_bf16 v[58:61], v[162:165], v[154:157], 0
	v_mfma_f32_16x16x32_bf16 v[54:57], v[170:173], v[146:149], 0
	v_mfma_f32_16x16x32_bf16 v[50:53], v[170:173], v[154:157], 0
	v_mfma_f32_16x16x32_bf16 v[46:49], v[180:183], v[146:149], 0
	v_mfma_f32_16x16x32_bf16 v[42:45], v[180:183], v[154:157], 0
	v_mfma_f32_16x16x32_bf16 v[38:41], v[188:191], v[146:149], 0
	v_mfma_f32_16x16x32_bf16 v[34:37], v[188:191], v[154:157], 0
	v_mfma_f32_16x16x32_bf16 v[62:65], v[166:169], v[150:153], v[62:65]
	v_mfma_f32_16x16x32_bf16 v[58:61], v[166:169], v[158:161], v[58:61]
	v_mfma_f32_16x16x32_bf16 v[54:57], v[174:177], v[150:153], v[54:57]
	v_mfma_f32_16x16x32_bf16 v[50:53], v[174:177], v[158:161], v[50:53]
	v_mfma_f32_16x16x32_bf16 v[46:49], v[184:187], v[150:153], v[46:49]
	v_mfma_f32_16x16x32_bf16 v[42:45], v[184:187], v[158:161], v[42:45]
	v_mfma_f32_16x16x32_bf16 v[38:41], v[192:195], v[150:153], v[38:41]
	v_mfma_f32_16x16x32_bf16 v[34:37], v[192:195], v[158:161], v[34:37]
	v_mfma_f32_16x16x32_bf16 v[30:33], v[162:165], v[196:199], 0
	v_mfma_f32_16x16x32_bf16 v[26:29], v[162:165], v[204:207], 0
	v_mfma_f32_16x16x32_bf16 v[22:25], v[170:173], v[196:199], 0
	v_mfma_f32_16x16x32_bf16 v[18:21], v[170:173], v[204:207], 0
	v_mfma_f32_16x16x32_bf16 v[14:17], v[180:183], v[196:199], 0
	v_mfma_f32_16x16x32_bf16 v[10:13], v[180:183], v[204:207], 0
	v_mfma_f32_16x16x32_bf16 v[6:9], v[188:191], v[196:199], 0
	v_mfma_f32_16x16x32_bf16 v[2:5], v[188:191], v[204:207], 0
	v_mfma_f32_16x16x32_bf16 v[30:33], v[166:169], v[200:203], v[30:33]
	v_mfma_f32_16x16x32_bf16 v[26:29], v[166:169], v[208:211], v[26:29]
	v_mfma_f32_16x16x32_bf16 v[22:25], v[174:177], v[200:203], v[22:25]
	v_mfma_f32_16x16x32_bf16 v[18:21], v[174:177], v[208:211], v[18:21]
	v_mfma_f32_16x16x32_bf16 v[14:17], v[184:187], v[200:203], v[14:17]
	v_mfma_f32_16x16x32_bf16 v[10:13], v[184:187], v[208:211], v[10:13]
	v_mfma_f32_16x16x32_bf16 v[6:9], v[192:195], v[200:203], v[6:9]
	v_mfma_f32_16x16x32_bf16 v[2:5], v[192:195], v[208:211], v[2:5]
	s_setprio 0
	s_barrier
; #define WAIT_V(n) asm volatile("s_waitcnt vmcnt(" #n ")" ::: "memory")
; #define WAIT_L(n) asm volatile("s_waitcnt lgkmcnt(" #n ")" ::: "memory")
; #define BAR __builtin_amdgcn_s_barrier()
; #define SCHED __builtin_amdgcn_sched_barrier(0)
; #define STG_A(b, h, kt) stage_half_s(lds0 + ((b) * 2 + (h)) * HT_B, ((h) ? A1 : Ap) + (kt) * BK, off0, off1)
; #define STG_B(b, h, kt) stage_half_s(lds0 + (4 + (b) * 2 + (h)) * HT_B, ((h) ? B1p : Bp) + (kt) * BK, off0, off1)
; #define STG_A(b, h, kt) stage_half_s(lds0 + ((b) * 2 + (h)) * HT_B, ((h) ? A1 : Ap) + (kt) * BK, off0, off1)
; #define STG_B(b, h, kt) stage_half_s(lds0 + (4 + (b) * 2 + (h)) * HT_B, ((h) ? B1p : Bp) + (kt) * BK, off0, off1)
; #define LDA8(b, h) _Pragma("unroll") for (int m = 0; m < 4; ++m) _Pragma("unroll") for (int k = 0; k < 2; ++k) \
;     At[m][k] = *(const bf16x8*)(SA_(shm, b, h) + abase + (m * 2 + k) * 1024)
; #define LDB8(dst, b, h) _Pragma("unroll") for (int n = 0; n < 2; ++n) _Pragma("unroll") for (int k = 0; k < 2; ++k) \
;     dst[n][k] = *(const bf16x8*)(SB_(shm, b, h) + bbase + (n * 2 + k) * 1024)
; #define MMA8(ai, bj, Bx) do { __builtin_amdgcn_s_setprio(1); \
;     _Pragma("unroll") for (int m = 0; m < 4; ++m) _Pragma("unroll") for (int n = 0; n < 2; ++n) _Pragma("unroll") for (int k = 0; k < 2; ++k) \
;       acc[ai][bj][m][n] = __builtin_amdgcn_mfma_f32_16x16x32_bf16(At[m][k], Bx[n][k], acc[ai][bj][m][n], 0, 0, 0); \
;     __builtin_amdgcn_s_setprio(0); } while (0)
; template <bool HS>
; __device__ __forceinline__ void gemm_tile8(const u16* __restrict__ Ap, const u16* __restrict__ Bp, int K,
;                                            f32x4 (&acc)[2][2][4][2], char* shm, const int tid, const float* hsr = nullptr) {
;     ...
;     LDB8(B0, 1, 0); SCHED; LDA8(1, 0); STG_A(0, 1, t + 2);
;     WAIT_L(8); BAR; WAIT_L(0); MMA8(0, 0, B0); BAR; SCHED;
;     LDB8(B1, 1, 1); STG_B(1, 0, t + 3);
;     BAR; WAIT_L(0); MMA8(0, 1, B1); BAR;
;     LDA8(1, 1); STG_A(1, 0, t + 3);
;     BAR; WAIT_L(0); MMA8(1, 0, B0); BAR; SCHED;
;     STG_B(1, 1, t + 3);
;     WAIT_V(6); BAR; MMA8(1, 1, B1); BAR;
;   }
	ds_read_b128 v[146:149], v246
	ds_read_b128 v[150:153], v246 offset:1024
	ds_read_b128 v[154:157], v246 offset:2048
	ds_read_b128 v[158:161], v246 offset:3072
	ds_read_b128 v[162:165], v142 offset:32768
	ds_read_b128 v[166:169], v142 offset:33792
	ds_read_b128 v[170:173], v142 offset:34816
	ds_read_b128 v[174:177], v142 offset:35840
	ds_read_b128 v[180:183], v142 offset:36864
	ds_read_b128 v[184:187], v142 offset:37888
	ds_read_b128 v[188:191], v142 offset:38912
	ds_read_b128 v[192:195], v142 offset:39936
	ds_read_b128 v[196:199], v247
	ds_read_b128 v[200:203], v247 offset:1024
	ds_read_b128 v[204:207], v247 offset:2048
	ds_read_b128 v[208:211], v247 offset:3072
	s_add_u32 s0, s18, 0x100
	s_addc_u32 s1, s19, 0
	s_add_i32 s3, s7, 0x4000
	s_mov_b32 m0, s3
	s_nop 0
	global_load_lds_dwordx4 v144, s[0:1]
	s_add_i32 s3, s7, 0x6000
	s_mov_b32 m0, s3
	s_nop 0
	global_load_lds_dwordx4 v143, s[0:1]
	s_waitcnt vmcnt(8) lgkmcnt(0)
	s_barrier
	s_setprio 1
	v_mfma_f32_16x16x32_bf16 v[126:129], v[162:165], v[146:149], v[126:129]
	v_mfma_f32_16x16x32_bf16 v[122:125], v[162:165], v[154:157], v[122:125]
	v_mfma_f32_16x16x32_bf16 v[118:121], v[170:173], v[146:149], v[118:121]
	v_mfma_f32_16x16x32_bf16 v[114:117], v[170:173], v[154:157], v[114:117]
	v_mfma_f32_16x16x32_bf16 v[110:113], v[180:183], v[146:149], v[110:113]
	v_mfma_f32_16x16x32_bf16 v[106:109], v[180:183], v[154:157], v[106:109]
	v_mfma_f32_16x16x32_bf16 v[102:105], v[188:191], v[146:149], v[102:105]
	v_mfma_f32_16x16x32_bf16 v[98:101], v[188:191], v[154:157], v[98:101]
	v_mfma_f32_16x16x32_bf16 v[126:129], v[166:169], v[150:153], v[126:129]
	v_mfma_f32_16x16x32_bf16 v[122:125], v[166:169], v[158:161], v[122:125]
	v_mfma_f32_16x16x32_bf16 v[118:121], v[174:177], v[150:153], v[118:121]
	v_mfma_f32_16x16x32_bf16 v[114:117], v[174:177], v[158:161], v[114:117]
	v_mfma_f32_16x16x32_bf16 v[110:113], v[184:187], v[150:153], v[110:113]
	v_mfma_f32_16x16x32_bf16 v[106:109], v[184:187], v[158:161], v[106:109]
	v_mfma_f32_16x16x32_bf16 v[102:105], v[192:195], v[150:153], v[102:105]
	v_mfma_f32_16x16x32_bf16 v[98:101], v[192:195], v[158:161], v[98:101]
	v_mfma_f32_16x16x32_bf16 v[94:97], v[162:165], v[196:199], v[94:97]
	v_mfma_f32_16x16x32_bf16 v[90:93], v[162:165], v[204:207], v[90:93]
	v_mfma_f32_16x16x32_bf16 v[86:89], v[170:173], v[196:199], v[86:89]
	v_mfma_f32_16x16x32_bf16 v[82:85], v[170:173], v[204:207], v[82:85]
	v_mfma_f32_16x16x32_bf16 v[78:81], v[180:183], v[196:199], v[78:81]
	v_mfma_f32_16x16x32_bf16 v[74:77], v[180:183], v[204:207], v[74:77]
	v_mfma_f32_16x16x32_bf16 v[70:73], v[188:191], v[196:199], v[70:73]
	v_mfma_f32_16x16x32_bf16 v[66:69], v[188:191], v[204:207], v[66:69]
	v_mfma_f32_16x16x32_bf16 v[94:97], v[166:169], v[200:203], v[94:97]
	v_mfma_f32_16x16x32_bf16 v[90:93], v[166:169], v[208:211], v[90:93]
	v_mfma_f32_16x16x32_bf16 v[86:89], v[174:177], v[200:203], v[86:89]
	v_mfma_f32_16x16x32_bf16 v[82:85], v[174:177], v[208:211], v[82:85]
	v_mfma_f32_16x16x32_bf16 v[78:81], v[184:187], v[200:203], v[78:81]
	v_mfma_f32_16x16x32_bf16 v[74:77], v[184:187], v[208:211], v[74:77]
	v_mfma_f32_16x16x32_bf16 v[70:73], v[192:195], v[200:203], v[70:73]
	v_mfma_f32_16x16x32_bf16 v[66:69], v[192:195], v[208:211], v[66:69]
	s_setprio 0
	s_barrier
	ds_read_b128 v[162:165], v142 offset:49152
	ds_read_b128 v[166:169], v142 offset:50176
	ds_read_b128 v[170:173], v142 offset:51200
	ds_read_b128 v[174:177], v142 offset:52224
	ds_read_b128 v[180:183], v142 offset:53248
	ds_read_b128 v[184:187], v142 offset:54272
	ds_read_b128 v[188:191], v142 offset:55296
	ds_read_b128 v[192:195], v142 offset:56320
	s_add_u32 s0, s20, 0x180
	s_addc_u32 s1, s21, 0
	s_add_i32 s3, s7, 0x18000
	s_mov_b32 m0, s3
	s_nop 0
	global_load_lds_dwordx4 v144, s[0:1]
	s_add_i32 s3, s7, 0x1a000
	s_mov_b32 m0, s3
	s_nop 0
	global_load_lds_dwordx4 v143, s[0:1]
	s_add_u32 s0, s16, 0x180
	s_addc_u32 s1, s17, 0
	s_add_i32 s3, s7, 0x8000
	s_mov_b32 m0, s3
	s_nop 0
	global_load_lds_dwordx4 v144, s[0:1]
	s_add_i32 s3, s7, 0xa000
	s_mov_b32 m0, s3
	s_nop 0
	global_load_lds_dwordx4 v143, s[0:1]
	s_add_u32 s0, s22, 0x180
	s_addc_u32 s1, s23, 0
	s_add_i32 s3, s7, 0x1c000
	s_mov_b32 m0, s3
	s_nop 0
	global_load_lds_dwordx4 v144, s[0:1]
	s_add_i32 s3, s7, 0x1e000
	s_mov_b32 m0, s3
	s_nop 0
	global_load_lds_dwordx4 v143, s[0:1]
	s_waitcnt vmcnt(8) lgkmcnt(0)
	s_barrier
	s_setprio 1
	v_mfma_f32_16x16x32_bf16 v[62:65], v[162:165], v[146:149], v[62:65]
	v_mfma_f32_16x16x32_bf16 v[58:61], v[162:165], v[154:157], v[58:61]
	v_mfma_f32_16x16x32_bf16 v[54:57], v[170:173], v[146:149], v[54:57]
	v_mfma_f32_16x16x32_bf16 v[50:53], v[170:173], v[154:157], v[50:53]
	v_mfma_f32_16x16x32_bf16 v[46:49], v[180:183], v[146:149], v[46:49]
	v_mfma_f32_16x16x32_bf16 v[42:45], v[180:183], v[154:157], v[42:45]
	v_mfma_f32_16x16x32_bf16 v[38:41], v[188:191], v[146:149], v[38:41]
	v_mfma_f32_16x16x32_bf16 v[34:37], v[188:191], v[154:157], v[34:37]
	v_mfma_f32_16x16x32_bf16 v[62:65], v[166:169], v[150:153], v[62:65]
	v_mfma_f32_16x16x32_bf16 v[58:61], v[166:169], v[158:161], v[58:61]
	v_mfma_f32_16x16x32_bf16 v[54:57], v[174:177], v[150:153], v[54:57]
	v_mfma_f32_16x16x32_bf16 v[50:53], v[174:177], v[158:161], v[50:53]
	v_mfma_f32_16x16x32_bf16 v[46:49], v[184:187], v[150:153], v[46:49]
	v_mfma_f32_16x16x32_bf16 v[42:45], v[184:187], v[158:161], v[42:45]
	v_mfma_f32_16x16x32_bf16 v[38:41], v[192:195], v[150:153], v[38:41]
	v_mfma_f32_16x16x32_bf16 v[34:37], v[192:195], v[158:161], v[34:37]
	v_mfma_f32_16x16x32_bf16 v[30:33], v[162:165], v[196:199], v[30:33]
	v_mfma_f32_16x16x32_bf16 v[26:29], v[162:165], v[204:207], v[26:29]
	v_mfma_f32_16x16x32_bf16 v[22:25], v[170:173], v[196:199], v[22:25]
	v_mfma_f32_16x16x32_bf16 v[18:21], v[170:173], v[204:207], v[18:21]
	v_mfma_f32_16x16x32_bf16 v[14:17], v[180:183], v[196:199], v[14:17]
	v_mfma_f32_16x16x32_bf16 v[10:13], v[180:183], v[204:207], v[10:13]
	v_mfma_f32_16x16x32_bf16 v[6:9], v[188:191], v[196:199], v[6:9]
	v_mfma_f32_16x16x32_bf16 v[2:5], v[188:191], v[204:207], v[2:5]
	v_mfma_f32_16x16x32_bf16 v[30:33], v[166:169], v[200:203], v[30:33]
	v_mfma_f32_16x16x32_bf16 v[26:29], v[166:169], v[208:211], v[26:29]
	v_mfma_f32_16x16x32_bf16 v[22:25], v[174:177], v[200:203], v[22:25]
	v_mfma_f32_16x16x32_bf16 v[18:21], v[174:177], v[208:211], v[18:21]
	v_mfma_f32_16x16x32_bf16 v[14:17], v[184:187], v[200:203], v[14:17]
	v_mfma_f32_16x16x32_bf16 v[10:13], v[184:187], v[208:211], v[10:13]
	v_mfma_f32_16x16x32_bf16 v[6:9], v[192:195], v[200:203], v[6:9]
	v_mfma_f32_16x16x32_bf16 v[2:5], v[192:195], v[208:211], v[2:5]
	s_setprio 0
	s_barrier
	s_add_u32 s16, s16, 0x100
	s_addc_u32 s17, s17, 0
	s_add_u32 s18, s18, 0x100
	s_addc_u32 s19, s19, 0
	s_add_u32 s20, s20, 0x100
	s_addc_u32 s21, s21, 0
	s_add_u32 s22, s22, 0x100
	s_addc_u32 s23, s23, 0
	s_mov_b32 s14, 6
; #define WAIT_V(n) asm volatile("s_waitcnt vmcnt(" #n ")" ::: "memory")
; #define WAIT_L(n) asm volatile("s_waitcnt lgkmcnt(" #n ")" ::: "memory")
; #define BAR __builtin_amdgcn_s_barrier()
; #define SCHED __builtin_amdgcn_sched_barrier(0)
; #define STG_A(b, h, kt) stage_half_s(lds0 + ((b) * 2 + (h)) * HT_B, ((h) ? A1 : Ap) + (kt) * BK, off0, off1)
; #define STG_B(b, h, kt) stage_half_s(lds0 + (4 + (b) * 2 + (h)) * HT_B, ((h) ? B1p : Bp) + (kt) * BK, off0, off1)
; #define STG_A(b, h, kt) stage_half_s(lds0 + ((b) * 2 + (h)) * HT_B, ((h) ? A1 : Ap) + (kt) * BK, off0, off1)
; #define STG_B(b, h, kt) stage_half_s(lds0 + (4 + (b) * 2 + (h)) * HT_B, ((h) ? B1p : Bp) + (kt) * BK, off0, off1)
; #define LDA8(b, h) _Pragma("unroll") for (int m = 0; m < 4; ++m) _Pragma("unroll") for (int k = 0; k < 2; ++k) \
;     At[m][k] = *(const bf16x8*)(SA_(shm, b, h) + abase + (m * 2 + k) * 1024)
; #define LDB8(dst, b, h) _Pragma("unroll") for (int n = 0; n < 2; ++n) _Pragma("unroll") for (int k = 0; k < 2; ++k) \
;     dst[n][k] = *(const bf16x8*)(SB_(shm, b, h) + bbase + (n * 2 + k) * 1024)
; #define MMA8(ai, bj, Bx) do { __builtin_amdgcn_s_setprio(1); \
;     _Pragma("unroll") for (int m = 0; m < 4; ++m) _Pragma("unroll") for (int n = 0; n < 2; ++n) _Pragma("unroll") for (int k = 0; k < 2; ++k) \
;       acc[ai][bj][m][n] = __builtin_amdgcn_mfma_f32_16x16x32_bf16(At[m][k], Bx[n][k], acc[ai][bj][m][n], 0, 0, 0); \
;     __builtin_amdgcn_s_setprio(0); } while (0)
; template <bool HS>
; __device__ __forceinline__ void gemm_tile8(const u16* __restrict__ Ap, const u16* __restrict__ Bp, int K,
;                                            f32x4 (&acc)[2][2][4][2], char* shm, const int tid, const float* hsr = nullptr) {
;     ...
;     LDB8(B0, 0, 0); SCHED; LDA8(0, 0); STG_A(1, 1, t + 1);
;     WAIT_L(8); BAR; WAIT_L(0); MMA8(0, 0, B0); BAR; SCHED;
;     LDB8(B1, 0, 1); STG_B(0, 0, t + 2);
;     BAR; WAIT_L(0); MMA8(0, 1, B1); BAR;
;     LDA8(0, 1); STG_A(0, 0, t + 2);
;     BAR; WAIT_L(0); MMA8(1, 0, B0); BAR; SCHED;
;     STG_B(0, 1, t + 2);
;     WAIT_V(6); BAR; MMA8(1, 1, B1); BAR;
.Lk_ffn_in:
	ds_read_b128 v[146:149], v244
	ds_read_b128 v[150:153], v244 offset:1024
	ds_read_b128 v[154:157], v244 offset:2048
	ds_read_b128 v[158:161], v244 offset:3072
	ds_read_b128 v[162:165], v142
	ds_read_b128 v[166:169], v142 offset:1024
	ds_read_b128 v[170:173], v142 offset:2048
	ds_read_b128 v[174:177], v142 offset:3072
	ds_read_b128 v[180:183], v142 offset:4096
	ds_read_b128 v[184:187], v142 offset:5120
	ds_read_b128 v[188:191], v142 offset:6144
	ds_read_b128 v[192:195], v142 offset:7168
	ds_read_b128 v[196:199], v245
	ds_read_b128 v[200:203], v245 offset:1024
	ds_read_b128 v[204:207], v245 offset:2048
	ds_read_b128 v[208:211], v245 offset:3072
	s_add_u32 s0, s18, 0x80
	s_addc_u32 s1, s19, 0
	s_add_i32 s3, s7, 0xc000
	s_mov_b32 m0, s3
	s_nop 0
	global_load_lds_dwordx4 v144, s[0:1]
	s_add_i32 s3, s7, 0xe000
	s_mov_b32 m0, s3
	s_nop 0
	global_load_lds_dwordx4 v143, s[0:1]
	s_waitcnt vmcnt(8) lgkmcnt(0)
	s_barrier
	s_setprio 1
	v_mfma_f32_16x16x32_bf16 v[126:129], v[162:165], v[146:149], v[126:129]
	v_mfma_f32_16x16x32_bf16 v[122:125], v[162:165], v[154:157], v[122:125]
	v_mfma_f32_16x16x32_bf16 v[118:121], v[170:173], v[146:149], v[118:121]
	v_mfma_f32_16x16x32_bf16 v[114:117], v[170:173], v[154:157], v[114:117]
	v_mfma_f32_16x16x32_bf16 v[110:113], v[180:183], v[146:149], v[110:113]
	v_mfma_f32_16x16x32_bf16 v[106:109], v[180:183], v[154:157], v[106:109]
	v_mfma_f32_16x16x32_bf16 v[102:105], v[188:191], v[146:149], v[102:105]
	v_mfma_f32_16x16x32_bf16 v[98:101], v[188:191], v[154:157], v[98:101]
	v_mfma_f32_16x16x32_bf16 v[126:129], v[166:169], v[150:153], v[126:129]
	v_mfma_f32_16x16x32_bf16 v[122:125], v[166:169], v[158:161], v[122:125]
	v_mfma_f32_16x16x32_bf16 v[118:121], v[174:177], v[150:153], v[118:121]
	v_mfma_f32_16x16x32_bf16 v[114:117], v[174:177], v[158:161], v[114:117]
	v_mfma_f32_16x16x32_bf16 v[110:113], v[184:187], v[150:153], v[110:113]
	v_mfma_f32_16x16x32_bf16 v[106:109], v[184:187], v[158:161], v[106:109]
	v_mfma_f32_16x16x32_bf16 v[102:105], v[192:195], v[150:153], v[102:105]
	v_mfma_f32_16x16x32_bf16 v[98:101], v[192:195], v[158:161], v[98:101]
	v_mfma_f32_16x16x32_bf16 v[94:97], v[162:165], v[196:199], v[94:97]
	v_mfma_f32_16x16x32_bf16 v[90:93], v[162:165], v[204:207], v[90:93]
	v_mfma_f32_16x16x32_bf16 v[86:89], v[170:173], v[196:199], v[86:89]
	v_mfma_f32_16x16x32_bf16 v[82:85], v[170:173], v[204:207], v[82:85]
	v_mfma_f32_16x16x32_bf16 v[78:81], v[180:183], v[196:199], v[78:81]
	v_mfma_f32_16x16x32_bf16 v[74:77], v[180:183], v[204:207], v[74:77]
	v_mfma_f32_16x16x32_bf16 v[70:73], v[188:191], v[196:199], v[70:73]
	v_mfma_f32_16x16x32_bf16 v[66:69], v[188:191], v[204:207], v[66:69]
	v_mfma_f32_16x16x32_bf16 v[94:97], v[166:169], v[200:203], v[94:97]
	v_mfma_f32_16x16x32_bf16 v[90:93], v[166:169], v[208:211], v[90:93]
	v_mfma_f32_16x16x32_bf16 v[86:89], v[174:177], v[200:203], v[86:89]
	v_mfma_f32_16x16x32_bf16 v[82:85], v[174:177], v[208:211], v[82:85]
	v_mfma_f32_16x16x32_bf16 v[78:81], v[184:187], v[200:203], v[78:81]
	v_mfma_f32_16x16x32_bf16 v[74:77], v[184:187], v[208:211], v[74:77]
	v_mfma_f32_16x16x32_bf16 v[70:73], v[192:195], v[200:203], v[70:73]
	v_mfma_f32_16x16x32_bf16 v[66:69], v[192:195], v[208:211], v[66:69]
	s_setprio 0
	s_barrier
	ds_read_b128 v[162:165], v142 offset:16384
	ds_read_b128 v[166:169], v142 offset:17408
	ds_read_b128 v[170:173], v142 offset:18432
	ds_read_b128 v[174:177], v142 offset:19456
	ds_read_b128 v[180:183], v142 offset:20480
	ds_read_b128 v[184:187], v142 offset:21504
	ds_read_b128 v[188:191], v142 offset:22528
	ds_read_b128 v[192:195], v142 offset:23552
	s_add_u32 s0, s20, 0x100
	s_addc_u32 s1, s21, 0
	s_add_i32 s3, s7, 0x10000
	s_mov_b32 m0, s3
	s_nop 0
	global_load_lds_dwordx4 v144, s[0:1]
	s_add_i32 s3, s7, 0x12000
	s_mov_b32 m0, s3
	s_nop 0
	global_load_lds_dwordx4 v143, s[0:1]
	s_add_u32 s0, s16, 0x100
	s_addc_u32 s1, s17, 0
	s_mov_b32 m0, s7
	s_nop 0
	global_load_lds_dwordx4 v144, s[0:1]
	s_add_i32 s3, s7, 0x2000
	s_mov_b32 m0, s3
	s_nop 0
	global_load_lds_dwordx4 v143, s[0:1]
	s_add_u32 s0, s22, 0x100
	s_addc_u32 s1, s23, 0
	s_add_i32 s3, s7, 0x14000
	s_mov_b32 m0, s3
	s_nop 0
	global_load_lds_dwordx4 v144, s[0:1]
	s_add_i32 s3, s7, 0x16000
	s_mov_b32 m0, s3
	s_nop 0
	global_load_lds_dwordx4 v143, s[0:1]
	s_waitcnt vmcnt(8) lgkmcnt(0)
	s_barrier
	s_setprio 1
	v_mfma_f32_16x16x32_bf16 v[62:65], v[162:165], v[146:149], v[62:65]
	v_mfma_f32_16x16x32_bf16 v[58:61], v[162:165], v[154:157], v[58:61]
	v_mfma_f32_16x16x32_bf16 v[54:57], v[170:173], v[146:149], v[54:57]
	v_mfma_f32_16x16x32_bf16 v[50:53], v[170:173], v[154:157], v[50:53]
	v_mfma_f32_16x16x32_bf16 v[46:49], v[180:183], v[146:149], v[46:49]
	v_mfma_f32_16x16x32_bf16 v[42:45], v[180:183], v[154:157], v[42:45]
	v_mfma_f32_16x16x32_bf16 v[38:41], v[188:191], v[146:149], v[38:41]
	v_mfma_f32_16x16x32_bf16 v[34:37], v[188:191], v[154:157], v[34:37]
	v_mfma_f32_16x16x32_bf16 v[62:65], v[166:169], v[150:153], v[62:65]
	v_mfma_f32_16x16x32_bf16 v[58:61], v[166:169], v[158:161], v[58:61]
	v_mfma_f32_16x16x32_bf16 v[54:57], v[174:177], v[150:153], v[54:57]
	v_mfma_f32_16x16x32_bf16 v[50:53], v[174:177], v[158:161], v[50:53]
	v_mfma_f32_16x16x32_bf16 v[46:49], v[184:187], v[150:153], v[46:49]
	v_mfma_f32_16x16x32_bf16 v[42:45], v[184:187], v[158:161], v[42:45]
	v_mfma_f32_16x16x32_bf16 v[38:41], v[192:195], v[150:153], v[38:41]
	v_mfma_f32_16x16x32_bf16 v[34:37], v[192:195], v[158:161], v[34:37]
	v_mfma_f32_16x16x32_bf16 v[30:33], v[162:165], v[196:199], v[30:33]
	v_mfma_f32_16x16x32_bf16 v[26:29], v[162:165], v[204:207], v[26:29]
	v_mfma_f32_16x16x32_bf16 v[22:25], v[170:173], v[196:199], v[22:25]
	v_mfma_f32_16x16x32_bf16 v[18:21], v[170:173], v[204:207], v[18:21]
	v_mfma_f32_16x16x32_bf16 v[14:17], v[180:183], v[196:199], v[14:17]
	v_mfma_f32_16x16x32_bf16 v[10:13], v[180:183], v[204:207], v[10:13]
	v_mfma_f32_16x16x32_bf16 v[6:9], v[188:191], v[196:199], v[6:9]
	v_mfma_f32_16x16x32_bf16 v[2:5], v[188:191], v[204:207], v[2:5]
	v_mfma_f32_16x16x32_bf16 v[30:33], v[166:169], v[200:203], v[30:33]
	v_mfma_f32_16x16x32_bf16 v[26:29], v[166:169], v[208:211], v[26:29]
	v_mfma_f32_16x16x32_bf16 v[22:25], v[174:177], v[200:203], v[22:25]
	v_mfma_f32_16x16x32_bf16 v[18:21], v[174:177], v[208:211], v[18:21]
	v_mfma_f32_16x16x32_bf16 v[14:17], v[184:187], v[200:203], v[14:17]
	v_mfma_f32_16x16x32_bf16 v[10:13], v[184:187], v[208:211], v[10:13]
	v_mfma_f32_16x16x32_bf16 v[6:9], v[192:195], v[200:203], v[6:9]
	v_mfma_f32_16x16x32_bf16 v[2:5], v[192:195], v[208:211], v[2:5]
	s_setprio 0
	s_barrier
; #define WAIT_V(n) asm volatile("s_waitcnt vmcnt(" #n ")" ::: "memory")
; #define WAIT_L(n) asm volatile("s_waitcnt lgkmcnt(" #n ")" ::: "memory")
; #define BAR __builtin_amdgcn_s_barrier()
; #define SCHED __builtin_amdgcn_sched_barrier(0)
; #define STG_A(b, h, kt) stage_half_s(lds0 + ((b) * 2 + (h)) * HT_B, ((h) ? A1 : Ap) + (kt) * BK, off0, off1)
; #define STG_B(b, h, kt) stage_half_s(lds0 + (4 + (b) * 2 + (h)) * HT_B, ((h) ? B1p : Bp) + (kt) * BK, off0, off1)
; #define STG_A(b, h, kt) stage_half_s(lds0 + ((b) * 2 + (h)) * HT_B, ((h) ? A1 : Ap) + (kt) * BK, off0, off1)
; #define STG_B(b, h, kt) stage_half_s(lds0 + (4 + (b) * 2 + (h)) * HT_B, ((h) ? B1p : Bp) + (kt) * BK, off0, off1)
; #define LDA8(b, h) _Pragma("unroll") for (int m = 0; m < 4; ++m) _Pragma("unroll") for (int k = 0; k < 2; ++k) \
;     At[m][k] = *(const bf16x8*)(SA_(shm, b, h) + abase + (m * 2 + k) * 1024)
; #define LDB8(dst, b, h) _Pragma("unroll") for (int n = 0; n < 2; ++n) _Pragma("unroll") for (int k = 0; k < 2; ++k) \
;     dst[n][k] = *(const bf16x8*)(SB_(shm, b, h) + bbase + (n * 2 + k) * 1024)
; #define MMA8(ai, bj, Bx) do { __builtin_amdgcn_s_setprio(1); \
;     _Pragma("unroll") for (int m = 0; m < 4; ++m) _Pragma("unroll") for (int n = 0; n < 2; ++n) _Pragma("unroll") for (int k = 0; k < 2; ++k) \
;       acc[ai][bj][m][n] = __builtin_amdgcn_mfma_f32_16x16x32_bf16(At[m][k], Bx[n][k], acc[ai][bj][m][n], 0, 0, 0); \
;     __builtin_amdgcn_s_setprio(0); } while (0)
; template <bool HS>
; __device__ __forceinline__ void gemm_tile8(const u16* __restrict__ Ap, const u16* __restrict__ Bp, int K,
;                                            f32x4 (&acc)[2][2][4][2], char* shm, const int tid, const float* hsr = nullptr) {
;     ...
;     LDB8(B0, 1, 0); SCHED; LDA8(1, 0); STG_A(0, 1, t + 2);
;     WAIT_L(8); BAR; WAIT_L(0); MMA8(0, 0, B0); BAR; SCHED;
;     LDB8(B1, 1, 1); STG_B(1, 0, t + 3);
;     BAR; WAIT_L(0); MMA8(0, 1, B1); BAR;
;     LDA8(1, 1); STG_A(1, 0, t + 3);
;     BAR; WAIT_L(0); MMA8(1, 0, B0); BAR; SCHED;
;     STG_B(1, 1, t + 3);
;     WAIT_V(6); BAR; MMA8(1, 1, B1); BAR;
	ds_read_b128 v[146:149], v246
	ds_read_b128 v[150:153], v246 offset:1024
	ds_read_b128 v[154:157], v246 offset:2048
	ds_read_b128 v[158:161], v246 offset:3072
	ds_read_b128 v[162:165], v142 offset:32768
	ds_read_b128 v[166:169], v142 offset:33792
	ds_read_b128 v[170:173], v142 offset:34816
	ds_read_b128 v[174:177], v142 offset:35840
	ds_read_b128 v[180:183], v142 offset:36864
	ds_read_b128 v[184:187], v142 offset:37888
	ds_read_b128 v[188:191], v142 offset:38912
	ds_read_b128 v[192:195], v142 offset:39936
	ds_read_b128 v[196:199], v247
	ds_read_b128 v[200:203], v247 offset:1024
	ds_read_b128 v[204:207], v247 offset:2048
	ds_read_b128 v[208:211], v247 offset:3072
	s_add_u32 s0, s18, 0x100
	s_addc_u32 s1, s19, 0
	s_add_i32 s3, s7, 0x4000
	s_mov_b32 m0, s3
	s_nop 0
	global_load_lds_dwordx4 v144, s[0:1]
	s_add_i32 s3, s7, 0x6000
	s_mov_b32 m0, s3
	s_nop 0
	global_load_lds_dwordx4 v143, s[0:1]
	s_waitcnt vmcnt(8) lgkmcnt(0)
	s_barrier
	s_setprio 1
	v_mfma_f32_16x16x32_bf16 v[126:129], v[162:165], v[146:149], v[126:129]
	v_mfma_f32_16x16x32_bf16 v[122:125], v[162:165], v[154:157], v[122:125]
	v_mfma_f32_16x16x32_bf16 v[118:121], v[170:173], v[146:149], v[118:121]
	v_mfma_f32_16x16x32_bf16 v[114:117], v[170:173], v[154:157], v[114:117]
	v_mfma_f32_16x16x32_bf16 v[110:113], v[180:183], v[146:149], v[110:113]
	v_mfma_f32_16x16x32_bf16 v[106:109], v[180:183], v[154:157], v[106:109]
	v_mfma_f32_16x16x32_bf16 v[102:105], v[188:191], v[146:149], v[102:105]
	v_mfma_f32_16x16x32_bf16 v[98:101], v[188:191], v[154:157], v[98:101]
	v_mfma_f32_16x16x32_bf16 v[126:129], v[166:169], v[150:153], v[126:129]
	v_mfma_f32_16x16x32_bf16 v[122:125], v[166:169], v[158:161], v[122:125]
	v_mfma_f32_16x16x32_bf16 v[118:121], v[174:177], v[150:153], v[118:121]
	v_mfma_f32_16x16x32_bf16 v[114:117], v[174:177], v[158:161], v[114:117]
	v_mfma_f32_16x16x32_bf16 v[110:113], v[184:187], v[150:153], v[110:113]
	v_mfma_f32_16x16x32_bf16 v[106:109], v[184:187], v[158:161], v[106:109]
	v_mfma_f32_16x16x32_bf16 v[102:105], v[192:195], v[150:153], v[102:105]
	v_mfma_f32_16x16x32_bf16 v[98:101], v[192:195], v[158:161], v[98:101]
	v_mfma_f32_16x16x32_bf16 v[94:97], v[162:165], v[196:199], v[94:97]
	v_mfma_f32_16x16x32_bf16 v[90:93], v[162:165], v[204:207], v[90:93]
	v_mfma_f32_16x16x32_bf16 v[86:89], v[170:173], v[196:199], v[86:89]
	v_mfma_f32_16x16x32_bf16 v[82:85], v[170:173], v[204:207], v[82:85]
	v_mfma_f32_16x16x32_bf16 v[78:81], v[180:183], v[196:199], v[78:81]
	v_mfma_f32_16x16x32_bf16 v[74:77], v[180:183], v[204:207], v[74:77]
	v_mfma_f32_16x16x32_bf16 v[70:73], v[188:191], v[196:199], v[70:73]
	v_mfma_f32_16x16x32_bf16 v[66:69], v[188:191], v[204:207], v[66:69]
	v_mfma_f32_16x16x32_bf16 v[94:97], v[166:169], v[200:203], v[94:97]
	v_mfma_f32_16x16x32_bf16 v[90:93], v[166:169], v[208:211], v[90:93]
	v_mfma_f32_16x16x32_bf16 v[86:89], v[174:177], v[200:203], v[86:89]
	v_mfma_f32_16x16x32_bf16 v[82:85], v[174:177], v[208:211], v[82:85]
	v_mfma_f32_16x16x32_bf16 v[78:81], v[184:187], v[200:203], v[78:81]
	v_mfma_f32_16x16x32_bf16 v[74:77], v[184:187], v[208:211], v[74:77]
	v_mfma_f32_16x16x32_bf16 v[70:73], v[192:195], v[200:203], v[70:73]
	v_mfma_f32_16x16x32_bf16 v[66:69], v[192:195], v[208:211], v[66:69]
	s_setprio 0
	s_barrier
	ds_read_b128 v[162:165], v142 offset:49152
	ds_read_b128 v[166:169], v142 offset:50176
	ds_read_b128 v[170:173], v142 offset:51200
	ds_read_b128 v[174:177], v142 offset:52224
	ds_read_b128 v[180:183], v142 offset:53248
	ds_read_b128 v[184:187], v142 offset:54272
	ds_read_b128 v[188:191], v142 offset:55296
	ds_read_b128 v[192:195], v142 offset:56320
	s_add_u32 s0, s20, 0x180
	s_addc_u32 s1, s21, 0
	s_add_i32 s3, s7, 0x18000
	s_mov_b32 m0, s3
	s_nop 0
	global_load_lds_dwordx4 v144, s[0:1]
	s_add_i32 s3, s7, 0x1a000
	s_mov_b32 m0, s3
	s_nop 0
	global_load_lds_dwordx4 v143, s[0:1]
	s_add_u32 s0, s16, 0x180
	s_addc_u32 s1, s17, 0
	s_add_i32 s3, s7, 0x8000
	s_mov_b32 m0, s3
	s_nop 0
	global_load_lds_dwordx4 v144, s[0:1]
	s_add_i32 s3, s7, 0xa000
	s_mov_b32 m0, s3
	s_nop 0
	global_load_lds_dwordx4 v143, s[0:1]
	s_add_u32 s0, s22, 0x180
	s_addc_u32 s1, s23, 0
	s_add_i32 s3, s7, 0x1c000
	s_mov_b32 m0, s3
	s_nop 0
	global_load_lds_dwordx4 v144, s[0:1]
	s_add_i32 s3, s7, 0x1e000
	s_mov_b32 m0, s3
	s_nop 0
	global_load_lds_dwordx4 v143, s[0:1]
	s_waitcnt vmcnt(8) lgkmcnt(0)
	s_barrier
	s_setprio 1
	v_mfma_f32_16x16x32_bf16 v[62:65], v[162:165], v[146:149], v[62:65]
	v_mfma_f32_16x16x32_bf16 v[58:61], v[162:165], v[154:157], v[58:61]
	v_mfma_f32_16x16x32_bf16 v[54:57], v[170:173], v[146:149], v[54:57]
	v_mfma_f32_16x16x32_bf16 v[50:53], v[170:173], v[154:157], v[50:53]
	v_mfma_f32_16x16x32_bf16 v[46:49], v[180:183], v[146:149], v[46:49]
	v_mfma_f32_16x16x32_bf16 v[42:45], v[180:183], v[154:157], v[42:45]
	v_mfma_f32_16x16x32_bf16 v[38:41], v[188:191], v[146:149], v[38:41]
	v_mfma_f32_16x16x32_bf16 v[34:37], v[188:191], v[154:157], v[34:37]
	v_mfma_f32_16x16x32_bf16 v[62:65], v[166:169], v[150:153], v[62:65]
	v_mfma_f32_16x16x32_bf16 v[58:61], v[166:169], v[158:161], v[58:61]
	v_mfma_f32_16x16x32_bf16 v[54:57], v[174:177], v[150:153], v[54:57]
	v_mfma_f32_16x16x32_bf16 v[50:53], v[174:177], v[158:161], v[50:53]
	v_mfma_f32_16x16x32_bf16 v[46:49], v[184:187], v[150:153], v[46:49]
	v_mfma_f32_16x16x32_bf16 v[42:45], v[184:187], v[158:161], v[42:45]
	v_mfma_f32_16x16x32_bf16 v[38:41], v[192:195], v[150:153], v[38:41]
	v_mfma_f32_16x16x32_bf16 v[34:37], v[192:195], v[158:161], v[34:37]
	v_mfma_f32_16x16x32_bf16 v[30:33], v[162:165], v[196:199], v[30:33]
	v_mfma_f32_16x16x32_bf16 v[26:29], v[162:165], v[204:207], v[26:29]
	v_mfma_f32_16x16x32_bf16 v[22:25], v[170:173], v[196:199], v[22:25]
	v_mfma_f32_16x16x32_bf16 v[18:21], v[170:173], v[204:207], v[18:21]
	v_mfma_f32_16x16x32_bf16 v[14:17], v[180:183], v[196:199], v[14:17]
	v_mfma_f32_16x16x32_bf16 v[10:13], v[180:183], v[204:207], v[10:13]
	v_mfma_f32_16x16x32_bf16 v[6:9], v[188:191], v[196:199], v[6:9]
	v_mfma_f32_16x16x32_bf16 v[2:5], v[188:191], v[204:207], v[2:5]
	v_mfma_f32_16x16x32_bf16 v[30:33], v[166:169], v[200:203], v[30:33]
	v_mfma_f32_16x16x32_bf16 v[26:29], v[166:169], v[208:211], v[26:29]
	v_mfma_f32_16x16x32_bf16 v[22:25], v[174:177], v[200:203], v[22:25]
	v_mfma_f32_16x16x32_bf16 v[18:21], v[174:177], v[208:211], v[18:21]
	v_mfma_f32_16x16x32_bf16 v[14:17], v[184:187], v[200:203], v[14:17]
	v_mfma_f32_16x16x32_bf16 v[10:13], v[184:187], v[208:211], v[10:13]
	v_mfma_f32_16x16x32_bf16 v[6:9], v[192:195], v[200:203], v[6:9]
	v_mfma_f32_16x16x32_bf16 v[2:5], v[192:195], v[208:211], v[2:5]
	s_setprio 0
	s_barrier
; #define WAIT_V(n) asm volatile("s_waitcnt vmcnt(" #n ")" ::: "memory")
; #define WAIT_L(n) asm volatile("s_waitcnt lgkmcnt(" #n ")" ::: "memory")
; #define BAR __builtin_amdgcn_s_barrier()
; #define STG_A(b, h, kt) stage_half_s(lds0 + ((b) * 2 + (h)) * HT_B, ((h) ? A1 : Ap) + (kt) * BK, off0, off1)
; #define STG_A(b, h, kt) stage_half_s(lds0 + ((b) * 2 + (h)) * HT_B, ((h) ? A1 : Ap) + (kt) * BK, off0, off1)
; #define LDA8(b, h) _Pragma("unroll") for (int m = 0; m < 4; ++m) _Pragma("unroll") for (int k = 0; k < 2; ++k) \
;     At[m][k] = *(const bf16x8*)(SA_(shm, b, h) + abase + (m * 2 + k) * 1024)
; #define LDB8(dst, b, h) _Pragma("unroll") for (int n = 0; n < 2; ++n) _Pragma("unroll") for (int k = 0; k < 2; ++k) \
;     dst[n][k] = *(const bf16x8*)(SB_(shm, b, h) + bbase + (n * 2 + k) * 1024)
; #define MMA8(ai, bj, Bx) do { __builtin_amdgcn_s_setprio(1); \
;     _Pragma("unroll") for (int m = 0; m < 4; ++m) _Pragma("unroll") for (int n = 0; n < 2; ++n) _Pragma("unroll") for (int k = 0; k < 2; ++k) \
;       acc[ai][bj][m][n] = __builtin_amdgcn_mfma_f32_16x16x32_bf16(At[m][k], Bx[n][k], acc[ai][bj][m][n], 0, 0, 0); \
;     __builtin_amdgcn_s_setprio(0); } while (0)
; template <bool HS>
; __device__ __forceinline__ void gemm_tile8(const u16* __restrict__ Ap, const u16* __restrict__ Bp, int K,
;                                            f32x4 (&acc)[2][2][4][2], char* shm, const int tid, const float* hsr = nullptr) {
;     ...
;     WAIT_V(6); BAR; MMA8(1, 1, B1); BAR;
;   }
;   { LDB8(B0, 0, 0); LDA8(0, 0); STG_A(1, 1, nt - 1);
;     BAR; WAIT_L(0); MMA8(0, 0, B0); BAR;
;     LDB8(B1, 0, 1); BAR; WAIT_L(0); MMA8(0, 1, B1); BAR;
;     LDA8(0, 1); WAIT_V(4); BAR; WAIT_L(0); MMA8(1, 0, B0); MMA8(1, 1, B1); BAR; }
	s_add_u32 s16, s16, 0x100
	s_addc_u32 s17, s17, 0
	s_add_u32 s18, s18, 0x100
	s_addc_u32 s19, s19, 0
	s_add_u32 s20, s20, 0x100
	s_addc_u32 s21, s21, 0
	s_add_u32 s22, s22, 0x100
	s_addc_u32 s23, s23, 0
	s_sub_i32 s14, s14, 1
	s_cmp_lg_u32 s14, 0
	s_cbranch_scc1 .Lk_ffn_in
	ds_read_b128 v[146:149], v244
	ds_read_b128 v[150:153], v244 offset:1024
	ds_read_b128 v[154:157], v244 offset:2048
	ds_read_b128 v[158:161], v244 offset:3072
	ds_read_b128 v[162:165], v142
	ds_read_b128 v[166:169], v142 offset:1024
	ds_read_b128 v[170:173], v142 offset:2048
	ds_read_b128 v[174:177], v142 offset:3072
	ds_read_b128 v[180:183], v142 offset:4096
	ds_read_b128 v[184:187], v142 offset:5120
	ds_read_b128 v[188:191], v142 offset:6144
	ds_read_b128 v[192:195], v142 offset:7168
	ds_read_b128 v[196:199], v245
	ds_read_b128 v[200:203], v245 offset:1024
	ds_read_b128 v[204:207], v245 offset:2048
	ds_read_b128 v[208:211], v245 offset:3072
	s_add_u32 s0, s18, 0x80
	s_addc_u32 s1, s19, 0
	s_add_i32 s3, s7, 0xc000
	s_mov_b32 m0, s3
	s_nop 0
	global_load_lds_dwordx4 v144, s[0:1]
	s_add_i32 s3, s7, 0xe000
	s_mov_b32 m0, s3
	s_nop 0
	global_load_lds_dwordx4 v143, s[0:1]
	s_waitcnt vmcnt(8) lgkmcnt(0)
	s_barrier
	s_setprio 1
	v_mfma_f32_16x16x32_bf16 v[126:129], v[162:165], v[146:149], v[126:129]
	v_mfma_f32_16x16x32_bf16 v[122:125], v[162:165], v[154:157], v[122:125]
	v_mfma_f32_16x16x32_bf16 v[118:121], v[170:173], v[146:149], v[118:121]
	v_mfma_f32_16x16x32_bf16 v[114:117], v[170:173], v[154:157], v[114:117]
	v_mfma_f32_16x16x32_bf16 v[110:113], v[180:183], v[146:149], v[110:113]
	v_mfma_f32_16x16x32_bf16 v[106:109], v[180:183], v[154:157], v[106:109]
	v_mfma_f32_16x16x32_bf16 v[102:105], v[188:191], v[146:149], v[102:105]
	v_mfma_f32_16x16x32_bf16 v[98:101], v[188:191], v[154:157], v[98:101]
	v_mfma_f32_16x16x32_bf16 v[126:129], v[166:169], v[150:153], v[126:129]
	v_mfma_f32_16x16x32_bf16 v[122:125], v[166:169], v[158:161], v[122:125]
	v_mfma_f32_16x16x32_bf16 v[118:121], v[174:177], v[150:153], v[118:121]
	v_mfma_f32_16x16x32_bf16 v[114:117], v[174:177], v[158:161], v[114:117]
	v_mfma_f32_16x16x32_bf16 v[110:113], v[184:187], v[150:153], v[110:113]
	v_mfma_f32_16x16x32_bf16 v[106:109], v[184:187], v[158:161], v[106:109]
	v_mfma_f32_16x16x32_bf16 v[102:105], v[192:195], v[150:153], v[102:105]
	v_mfma_f32_16x16x32_bf16 v[98:101], v[192:195], v[158:161], v[98:101]
	v_mfma_f32_16x16x32_bf16 v[94:97], v[162:165], v[196:199], v[94:97]
	v_mfma_f32_16x16x32_bf16 v[90:93], v[162:165], v[204:207], v[90:93]
	v_mfma_f32_16x16x32_bf16 v[86:89], v[170:173], v[196:199], v[86:89]
	v_mfma_f32_16x16x32_bf16 v[82:85], v[170:173], v[204:207], v[82:85]
	v_mfma_f32_16x16x32_bf16 v[78:81], v[180:183], v[196:199], v[78:81]
	v_mfma_f32_16x16x32_bf16 v[74:77], v[180:183], v[204:207], v[74:77]
	v_mfma_f32_16x16x32_bf16 v[70:73], v[188:191], v[196:199], v[70:73]
	v_mfma_f32_16x16x32_bf16 v[66:69], v[188:191], v[204:207], v[66:69]
	v_mfma_f32_16x16x32_bf16 v[94:97], v[166:169], v[200:203], v[94:97]
	v_mfma_f32_16x16x32_bf16 v[90:93], v[166:169], v[208:211], v[90:93]
	v_mfma_f32_16x16x32_bf16 v[86:89], v[174:177], v[200:203], v[86:89]
	v_mfma_f32_16x16x32_bf16 v[82:85], v[174:177], v[208:211], v[82:85]
	v_mfma_f32_16x16x32_bf16 v[78:81], v[184:187], v[200:203], v[78:81]
	v_mfma_f32_16x16x32_bf16 v[74:77], v[184:187], v[208:211], v[74:77]
	v_mfma_f32_16x16x32_bf16 v[70:73], v[192:195], v[200:203], v[70:73]
	v_mfma_f32_16x16x32_bf16 v[66:69], v[192:195], v[208:211], v[66:69]
	s_setprio 0
	s_barrier
	ds_read_b128 v[162:165], v142 offset:16384
	ds_read_b128 v[166:169], v142 offset:17408
	ds_read_b128 v[170:173], v142 offset:18432
	ds_read_b128 v[174:177], v142 offset:19456
	ds_read_b128 v[180:183], v142 offset:20480
	ds_read_b128 v[184:187], v142 offset:21504
	ds_read_b128 v[188:191], v142 offset:22528
	ds_read_b128 v[192:195], v142 offset:23552
	s_waitcnt vmcnt(2) lgkmcnt(0)
	s_barrier
	s_setprio 1
	v_mfma_f32_16x16x32_bf16 v[62:65], v[162:165], v[146:149], v[62:65]
	v_mfma_f32_16x16x32_bf16 v[58:61], v[162:165], v[154:157], v[58:61]
	v_mfma_f32_16x16x32_bf16 v[54:57], v[170:173], v[146:149], v[54:57]
	v_mfma_f32_16x16x32_bf16 v[50:53], v[170:173], v[154:157], v[50:53]
	v_mfma_f32_16x16x32_bf16 v[46:49], v[180:183], v[146:149], v[46:49]
	v_mfma_f32_16x16x32_bf16 v[42:45], v[180:183], v[154:157], v[42:45]
	v_mfma_f32_16x16x32_bf16 v[38:41], v[188:191], v[146:149], v[38:41]
	v_mfma_f32_16x16x32_bf16 v[34:37], v[188:191], v[154:157], v[34:37]
	v_mfma_f32_16x16x32_bf16 v[62:65], v[166:169], v[150:153], v[62:65]
	v_mfma_f32_16x16x32_bf16 v[58:61], v[166:169], v[158:161], v[58:61]
	v_mfma_f32_16x16x32_bf16 v[54:57], v[174:177], v[150:153], v[54:57]
	v_mfma_f32_16x16x32_bf16 v[50:53], v[174:177], v[158:161], v[50:53]
	v_mfma_f32_16x16x32_bf16 v[46:49], v[184:187], v[150:153], v[46:49]
	v_mfma_f32_16x16x32_bf16 v[42:45], v[184:187], v[158:161], v[42:45]
	v_mfma_f32_16x16x32_bf16 v[38:41], v[192:195], v[150:153], v[38:41]
	v_mfma_f32_16x16x32_bf16 v[34:37], v[192:195], v[158:161], v[34:37]
	v_mfma_f32_16x16x32_bf16 v[30:33], v[162:165], v[196:199], v[30:33]
	v_mfma_f32_16x16x32_bf16 v[26:29], v[162:165], v[204:207], v[26:29]
	v_mfma_f32_16x16x32_bf16 v[22:25], v[170:173], v[196:199], v[22:25]
	v_mfma_f32_16x16x32_bf16 v[18:21], v[170:173], v[204:207], v[18:21]
	v_mfma_f32_16x16x32_bf16 v[14:17], v[180:183], v[196:199], v[14:17]
	v_mfma_f32_16x16x32_bf16 v[10:13], v[180:183], v[204:207], v[10:13]
	v_mfma_f32_16x16x32_bf16 v[6:9], v[188:191], v[196:199], v[6:9]
	v_mfma_f32_16x16x32_bf16 v[2:5], v[188:191], v[204:207], v[2:5]
	v_mfma_f32_16x16x32_bf16 v[30:33], v[166:169], v[200:203], v[30:33]
	v_mfma_f32_16x16x32_bf16 v[26:29], v[166:169], v[208:211], v[26:29]
	v_mfma_f32_16x16x32_bf16 v[22:25], v[174:177], v[200:203], v[22:25]
	v_mfma_f32_16x16x32_bf16 v[18:21], v[174:177], v[208:211], v[18:21]
	v_mfma_f32_16x16x32_bf16 v[14:17], v[184:187], v[200:203], v[14:17]
	v_mfma_f32_16x16x32_bf16 v[10:13], v[184:187], v[208:211], v[10:13]
	v_mfma_f32_16x16x32_bf16 v[6:9], v[192:195], v[200:203], v[6:9]
	v_mfma_f32_16x16x32_bf16 v[2:5], v[192:195], v[208:211], v[2:5]
	s_setprio 0
	s_barrier
; #define WAIT_V(n) asm volatile("s_waitcnt vmcnt(" #n ")" ::: "memory")
; #define WAIT_L(n) asm volatile("s_waitcnt lgkmcnt(" #n ")" ::: "memory")
; #define BAR __builtin_amdgcn_s_barrier()
; #define LDA8(b, h) _Pragma("unroll") for (int m = 0; m < 4; ++m) _Pragma("unroll") for (int k = 0; k < 2; ++k) \
;     At[m][k] = *(const bf16x8*)(SA_(shm, b, h) + abase + (m * 2 + k) * 1024)
; #define LDB8(dst, b, h) _Pragma("unroll") for (int n = 0; n < 2; ++n) _Pragma("unroll") for (int k = 0; k < 2; ++k) \
;     dst[n][k] = *(const bf16x8*)(SB_(shm, b, h) + bbase + (n * 2 + k) * 1024)
; #define MMA8(ai, bj, Bx) do { __builtin_amdgcn_s_setprio(1); \
;     _Pragma("unroll") for (int m = 0; m < 4; ++m) _Pragma("unroll") for (int n = 0; n < 2; ++n) _Pragma("unroll") for (int k = 0; k < 2; ++k) \
;       acc[ai][bj][m][n] = __builtin_amdgcn_mfma_f32_16x16x32_bf16(At[m][k], Bx[n][k], acc[ai][bj][m][n], 0, 0, 0); \
;     __builtin_amdgcn_s_setprio(0); } while (0)
; template <bool HS>
; __device__ __forceinline__ void gemm_tile8(const u16* __restrict__ Ap, const u16* __restrict__ Bp, int K,
;                                            f32x4 (&acc)[2][2][4][2], char* shm, const int tid, const float* hsr = nullptr) {
;     ...
;   { LDB8(B0, 1, 0); LDA8(1, 0); WAIT_V(2); BAR; WAIT_L(0); MMA8(0, 0, B0); BAR;
;     LDB8(B1, 1, 1); WAIT_V(0); BAR; WAIT_L(0); MMA8(0, 1, B1); BAR;
;     LDA8(1, 1); BAR; WAIT_L(0); MMA8(1, 0, B0); MMA8(1, 1, B1); BAR; }
;   if (wr == 0) BAR;
	ds_read_b128 v[146:149], v246
	ds_read_b128 v[150:153], v246 offset:1024
	ds_read_b128 v[154:157], v246 offset:2048
	ds_read_b128 v[158:161], v246 offset:3072
	ds_read_b128 v[162:165], v142 offset:32768
	ds_read_b128 v[166:169], v142 offset:33792
	ds_read_b128 v[170:173], v142 offset:34816
	ds_read_b128 v[174:177], v142 offset:35840
	ds_read_b128 v[180:183], v142 offset:36864
	ds_read_b128 v[184:187], v142 offset:37888
	ds_read_b128 v[188:191], v142 offset:38912
	ds_read_b128 v[192:195], v142 offset:39936
	ds_read_b128 v[196:199], v247
	ds_read_b128 v[200:203], v247 offset:1024
	ds_read_b128 v[204:207], v247 offset:2048
	ds_read_b128 v[208:211], v247 offset:3072
	s_waitcnt vmcnt(0) lgkmcnt(0)
	s_barrier
	s_setprio 1
	v_mfma_f32_16x16x32_bf16 v[126:129], v[162:165], v[146:149], v[126:129]
	v_mfma_f32_16x16x32_bf16 v[122:125], v[162:165], v[154:157], v[122:125]
	v_mfma_f32_16x16x32_bf16 v[118:121], v[170:173], v[146:149], v[118:121]
	v_mfma_f32_16x16x32_bf16 v[114:117], v[170:173], v[154:157], v[114:117]
	v_mfma_f32_16x16x32_bf16 v[110:113], v[180:183], v[146:149], v[110:113]
	v_mfma_f32_16x16x32_bf16 v[106:109], v[180:183], v[154:157], v[106:109]
	v_mfma_f32_16x16x32_bf16 v[102:105], v[188:191], v[146:149], v[102:105]
	v_mfma_f32_16x16x32_bf16 v[98:101], v[188:191], v[154:157], v[98:101]
	v_mfma_f32_16x16x32_bf16 v[126:129], v[166:169], v[150:153], v[126:129]
	v_mfma_f32_16x16x32_bf16 v[122:125], v[166:169], v[158:161], v[122:125]
	v_mfma_f32_16x16x32_bf16 v[118:121], v[174:177], v[150:153], v[118:121]
	v_mfma_f32_16x16x32_bf16 v[114:117], v[174:177], v[158:161], v[114:117]
	v_mfma_f32_16x16x32_bf16 v[110:113], v[184:187], v[150:153], v[110:113]
	v_mfma_f32_16x16x32_bf16 v[106:109], v[184:187], v[158:161], v[106:109]
	v_mfma_f32_16x16x32_bf16 v[102:105], v[192:195], v[150:153], v[102:105]
	v_mfma_f32_16x16x32_bf16 v[98:101], v[192:195], v[158:161], v[98:101]
	v_mfma_f32_16x16x32_bf16 v[94:97], v[162:165], v[196:199], v[94:97]
	v_mfma_f32_16x16x32_bf16 v[90:93], v[162:165], v[204:207], v[90:93]
	v_mfma_f32_16x16x32_bf16 v[86:89], v[170:173], v[196:199], v[86:89]
	v_mfma_f32_16x16x32_bf16 v[82:85], v[170:173], v[204:207], v[82:85]
	v_mfma_f32_16x16x32_bf16 v[78:81], v[180:183], v[196:199], v[78:81]
	v_mfma_f32_16x16x32_bf16 v[74:77], v[180:183], v[204:207], v[74:77]
	v_mfma_f32_16x16x32_bf16 v[70:73], v[188:191], v[196:199], v[70:73]
	v_mfma_f32_16x16x32_bf16 v[66:69], v[188:191], v[204:207], v[66:69]
	v_mfma_f32_16x16x32_bf16 v[94:97], v[166:169], v[200:203], v[94:97]
	v_mfma_f32_16x16x32_bf16 v[90:93], v[166:169], v[208:211], v[90:93]
	v_mfma_f32_16x16x32_bf16 v[86:89], v[174:177], v[200:203], v[86:89]
	v_mfma_f32_16x16x32_bf16 v[82:85], v[174:177], v[208:211], v[82:85]
	v_mfma_f32_16x16x32_bf16 v[78:81], v[184:187], v[200:203], v[78:81]
	v_mfma_f32_16x16x32_bf16 v[74:77], v[184:187], v[208:211], v[74:77]
	v_mfma_f32_16x16x32_bf16 v[70:73], v[192:195], v[200:203], v[70:73]
	v_mfma_f32_16x16x32_bf16 v[66:69], v[192:195], v[208:211], v[66:69]
	s_setprio 0
	s_barrier
	ds_read_b128 v[162:165], v142 offset:49152
	ds_read_b128 v[166:169], v142 offset:50176
	ds_read_b128 v[170:173], v142 offset:51200
	ds_read_b128 v[174:177], v142 offset:52224
	ds_read_b128 v[180:183], v142 offset:53248
	ds_read_b128 v[184:187], v142 offset:54272
	ds_read_b128 v[188:191], v142 offset:55296
	ds_read_b128 v[192:195], v142 offset:56320
	s_waitcnt lgkmcnt(0)
	s_barrier
	s_setprio 1
	v_mfma_f32_16x16x32_bf16 v[62:65], v[162:165], v[146:149], v[62:65]
	v_mfma_f32_16x16x32_bf16 v[58:61], v[162:165], v[154:157], v[58:61]
	v_mfma_f32_16x16x32_bf16 v[54:57], v[170:173], v[146:149], v[54:57]
	v_mfma_f32_16x16x32_bf16 v[50:53], v[170:173], v[154:157], v[50:53]
	v_mfma_f32_16x16x32_bf16 v[46:49], v[180:183], v[146:149], v[46:49]
	v_mfma_f32_16x16x32_bf16 v[42:45], v[180:183], v[154:157], v[42:45]
	v_mfma_f32_16x16x32_bf16 v[38:41], v[188:191], v[146:149], v[38:41]
	v_mfma_f32_16x16x32_bf16 v[34:37], v[188:191], v[154:157], v[34:37]
	v_mfma_f32_16x16x32_bf16 v[62:65], v[166:169], v[150:153], v[62:65]
	v_mfma_f32_16x16x32_bf16 v[58:61], v[166:169], v[158:161], v[58:61]
	v_mfma_f32_16x16x32_bf16 v[54:57], v[174:177], v[150:153], v[54:57]
	v_mfma_f32_16x16x32_bf16 v[50:53], v[174:177], v[158:161], v[50:53]
	v_mfma_f32_16x16x32_bf16 v[46:49], v[184:187], v[150:153], v[46:49]
	v_mfma_f32_16x16x32_bf16 v[42:45], v[184:187], v[158:161], v[42:45]
	v_mfma_f32_16x16x32_bf16 v[38:41], v[192:195], v[150:153], v[38:41]
	v_mfma_f32_16x16x32_bf16 v[34:37], v[192:195], v[158:161], v[34:37]
	v_mfma_f32_16x16x32_bf16 v[30:33], v[162:165], v[196:199], v[30:33]
	v_mfma_f32_16x16x32_bf16 v[26:29], v[162:165], v[204:207], v[26:29]
	v_mfma_f32_16x16x32_bf16 v[22:25], v[170:173], v[196:199], v[22:25]
	v_mfma_f32_16x16x32_bf16 v[18:21], v[170:173], v[204:207], v[18:21]
	v_mfma_f32_16x16x32_bf16 v[14:17], v[180:183], v[196:199], v[14:17]
	v_mfma_f32_16x16x32_bf16 v[10:13], v[180:183], v[204:207], v[10:13]
	v_mfma_f32_16x16x32_bf16 v[6:9], v[188:191], v[196:199], v[6:9]
	v_mfma_f32_16x16x32_bf16 v[2:5], v[188:191], v[204:207], v[2:5]
	v_mfma_f32_16x16x32_bf16 v[30:33], v[166:169], v[200:203], v[30:33]
	v_mfma_f32_16x16x32_bf16 v[26:29], v[166:169], v[208:211], v[26:29]
	v_mfma_f32_16x16x32_bf16 v[22:25], v[174:177], v[200:203], v[22:25]
	v_mfma_f32_16x16x32_bf16 v[18:21], v[174:177], v[208:211], v[18:21]
	v_mfma_f32_16x16x32_bf16 v[14:17], v[184:187], v[200:203], v[14:17]
	v_mfma_f32_16x16x32_bf16 v[10:13], v[184:187], v[208:211], v[10:13]
	v_mfma_f32_16x16x32_bf16 v[6:9], v[192:195], v[200:203], v[6:9]
	v_mfma_f32_16x16x32_bf16 v[2:5], v[192:195], v[208:211], v[2:5]
	s_setprio 0
	s_movk_i32 s0, 0x100
	v_cmp_gt_u32_e32 vcc, s0, v0
	s_barrier
	s_and_saveexec_b64 s[0:1], vcc
	s_cbranch_execz .LBB0_862
	s_barrier
